# GEMM unit head: accumulators zeroed once (64 v_mov_b64) instead of twice (256 v_mov) in all 7 GEMM phases
# speedup vs baseline: 1.0056x; 1.0056x over previous
.LBB0_212:
	s_andn2_b64 vcc, exec, s[78:79]
	s_cbranch_vccnz .LBB0_215
	s_add_u32 s4, s92, 0x80
	s_addc_u32 s5, s93, 0
	s_add_u32 s64, s96, 0x100
	s_addc_u32 s65, s97, 0
	s_mov_b32 s92, 0
	v_mov_b64_e32 v[0:1], 0
	v_mov_b64_e32 v[2:3], 0
	v_mov_b64_e32 v[4:5], 0
	v_mov_b64_e32 v[6:7], 0
	v_mov_b64_e32 v[8:9], 0
	v_mov_b64_e32 v[10:11], 0
	v_mov_b64_e32 v[12:13], 0
	v_mov_b64_e32 v[14:15], 0
	v_mov_b64_e32 v[16:17], 0
	v_mov_b64_e32 v[18:19], 0
	v_mov_b64_e32 v[20:21], 0
	v_mov_b64_e32 v[22:23], 0
	v_mov_b64_e32 v[24:25], 0
	v_mov_b64_e32 v[26:27], 0
	v_mov_b64_e32 v[28:29], 0
	v_mov_b64_e32 v[30:31], 0
	v_mov_b64_e32 v[32:33], 0
	v_mov_b64_e32 v[34:35], 0
	v_mov_b64_e32 v[36:37], 0
	v_mov_b64_e32 v[38:39], 0
	v_mov_b64_e32 v[40:41], 0
	v_mov_b64_e32 v[42:43], 0
	v_mov_b64_e32 v[44:45], 0
	v_mov_b64_e32 v[46:47], 0
	v_mov_b64_e32 v[48:49], 0
	v_mov_b64_e32 v[50:51], 0
	v_mov_b64_e32 v[52:53], 0
	v_mov_b64_e32 v[54:55], 0
	v_mov_b64_e32 v[56:57], 0
	v_mov_b64_e32 v[58:59], 0
	v_mov_b64_e32 v[60:61], 0
	v_mov_b64_e32 v[62:63], 0
	v_mov_b64_e32 v[64:65], 0
	v_mov_b64_e32 v[66:67], 0
	v_mov_b64_e32 v[68:69], 0
	v_mov_b64_e32 v[70:71], 0
	v_mov_b64_e32 v[72:73], 0
	v_mov_b64_e32 v[74:75], 0
	v_mov_b64_e32 v[76:77], 0
	v_mov_b64_e32 v[78:79], 0
	v_mov_b64_e32 v[80:81], 0
	v_mov_b64_e32 v[82:83], 0
	v_mov_b64_e32 v[84:85], 0
	v_mov_b64_e32 v[86:87], 0
	v_mov_b64_e32 v[88:89], 0
	v_mov_b64_e32 v[90:91], 0
	v_mov_b64_e32 v[92:93], 0
	v_mov_b64_e32 v[94:95], 0
	v_mov_b64_e32 v[96:97], 0
	v_mov_b64_e32 v[98:99], 0
	v_mov_b64_e32 v[100:101], 0
	v_mov_b64_e32 v[102:103], 0
	v_mov_b64_e32 v[104:105], 0
	v_mov_b64_e32 v[106:107], 0
	v_mov_b64_e32 v[108:109], 0
	v_mov_b64_e32 v[110:111], 0
	v_mov_b64_e32 v[112:113], 0
	v_mov_b64_e32 v[114:115], 0
	v_mov_b64_e32 v[116:117], 0
	v_mov_b64_e32 v[118:119], 0
	v_mov_b64_e32 v[120:121], 0
	v_mov_b64_e32 v[122:123], 0
	v_mov_b64_e32 v[124:125], 0
	v_mov_b64_e32 v[126:127], 0

.LBB0_391:
	s_andn2_b64 vcc, exec, s[78:79]
	s_cbranch_vccnz .LBB0_394
	s_add_u32 s84, s84, 0x80
	s_addc_u32 s85, s85, 0
	s_add_u32 vcc_lo, s10, 0x100
	s_addc_u32 vcc_hi, s11, 0
	s_mov_b32 s10, 0
	v_mov_b64_e32 v[0:1], 0
	v_mov_b64_e32 v[2:3], 0
	v_mov_b64_e32 v[4:5], 0
	v_mov_b64_e32 v[6:7], 0
	v_mov_b64_e32 v[8:9], 0
	v_mov_b64_e32 v[10:11], 0
	v_mov_b64_e32 v[12:13], 0
	v_mov_b64_e32 v[14:15], 0
	v_mov_b64_e32 v[16:17], 0
	v_mov_b64_e32 v[18:19], 0
	v_mov_b64_e32 v[20:21], 0
	v_mov_b64_e32 v[22:23], 0
	v_mov_b64_e32 v[24:25], 0
	v_mov_b64_e32 v[26:27], 0
	v_mov_b64_e32 v[28:29], 0
	v_mov_b64_e32 v[30:31], 0
	v_mov_b64_e32 v[32:33], 0
	v_mov_b64_e32 v[34:35], 0
	v_mov_b64_e32 v[36:37], 0
	v_mov_b64_e32 v[38:39], 0
	v_mov_b64_e32 v[40:41], 0
	v_mov_b64_e32 v[42:43], 0
	v_mov_b64_e32 v[44:45], 0
	v_mov_b64_e32 v[46:47], 0
	v_mov_b64_e32 v[48:49], 0
	v_mov_b64_e32 v[50:51], 0
	v_mov_b64_e32 v[52:53], 0
	v_mov_b64_e32 v[54:55], 0
	v_mov_b64_e32 v[56:57], 0
	v_mov_b64_e32 v[58:59], 0
	v_mov_b64_e32 v[60:61], 0
	v_mov_b64_e32 v[62:63], 0
	v_mov_b64_e32 v[64:65], 0
	v_mov_b64_e32 v[66:67], 0
	v_mov_b64_e32 v[68:69], 0
	v_mov_b64_e32 v[70:71], 0
	v_mov_b64_e32 v[72:73], 0
	v_mov_b64_e32 v[74:75], 0
	v_mov_b64_e32 v[76:77], 0
	v_mov_b64_e32 v[78:79], 0
	v_mov_b64_e32 v[80:81], 0
	v_mov_b64_e32 v[82:83], 0
	v_mov_b64_e32 v[84:85], 0
	v_mov_b64_e32 v[86:87], 0
	v_mov_b64_e32 v[88:89], 0
	v_mov_b64_e32 v[90:91], 0
	v_mov_b64_e32 v[92:93], 0
	v_mov_b64_e32 v[94:95], 0
	v_mov_b64_e32 v[96:97], 0
	v_mov_b64_e32 v[98:99], 0
	v_mov_b64_e32 v[100:101], 0
	v_mov_b64_e32 v[102:103], 0
	v_mov_b64_e32 v[104:105], 0
	v_mov_b64_e32 v[106:107], 0
	v_mov_b64_e32 v[108:109], 0
	v_mov_b64_e32 v[110:111], 0
	v_mov_b64_e32 v[112:113], 0
	v_mov_b64_e32 v[114:115], 0
	v_mov_b64_e32 v[116:117], 0
	v_mov_b64_e32 v[118:119], 0
	v_mov_b64_e32 v[120:121], 0
	v_mov_b64_e32 v[122:123], 0
	v_mov_b64_e32 v[124:125], 0
	v_mov_b64_e32 v[126:127], 0

.LBB0_478:
	s_andn2_b64 vcc, exec, s[38:39]
	s_cbranch_vccnz .LBB0_481
	s_add_u32 s52, s10, 0x80
	s_addc_u32 s53, s11, 0
	s_add_u32 s72, s72, 0x100
	s_addc_u32 s73, s73, 0
	s_mov_b32 s10, 0
	v_mov_b64_e32 v[0:1], 0
	v_mov_b64_e32 v[2:3], 0
	v_mov_b64_e32 v[4:5], 0
	v_mov_b64_e32 v[6:7], 0
	v_mov_b64_e32 v[8:9], 0
	v_mov_b64_e32 v[10:11], 0
	v_mov_b64_e32 v[12:13], 0
	v_mov_b64_e32 v[14:15], 0
	v_mov_b64_e32 v[16:17], 0
	v_mov_b64_e32 v[18:19], 0
	v_mov_b64_e32 v[20:21], 0
	v_mov_b64_e32 v[22:23], 0
	v_mov_b64_e32 v[24:25], 0
	v_mov_b64_e32 v[26:27], 0
	v_mov_b64_e32 v[28:29], 0
	v_mov_b64_e32 v[30:31], 0
	v_mov_b64_e32 v[32:33], 0
	v_mov_b64_e32 v[34:35], 0
	v_mov_b64_e32 v[36:37], 0
	v_mov_b64_e32 v[38:39], 0
	v_mov_b64_e32 v[40:41], 0
	v_mov_b64_e32 v[42:43], 0
	v_mov_b64_e32 v[44:45], 0
	v_mov_b64_e32 v[46:47], 0
	v_mov_b64_e32 v[48:49], 0
	v_mov_b64_e32 v[50:51], 0
	v_mov_b64_e32 v[52:53], 0
	v_mov_b64_e32 v[54:55], 0
	v_mov_b64_e32 v[56:57], 0
	v_mov_b64_e32 v[58:59], 0
	v_mov_b64_e32 v[60:61], 0
	v_mov_b64_e32 v[62:63], 0
	v_mov_b64_e32 v[64:65], 0
	v_mov_b64_e32 v[66:67], 0
	v_mov_b64_e32 v[68:69], 0
	v_mov_b64_e32 v[70:71], 0
	v_mov_b64_e32 v[72:73], 0
	v_mov_b64_e32 v[74:75], 0
	v_mov_b64_e32 v[76:77], 0
	v_mov_b64_e32 v[78:79], 0
	v_mov_b64_e32 v[80:81], 0
	v_mov_b64_e32 v[82:83], 0
	v_mov_b64_e32 v[84:85], 0
	v_mov_b64_e32 v[86:87], 0
	v_mov_b64_e32 v[88:89], 0
	v_mov_b64_e32 v[90:91], 0
	v_mov_b64_e32 v[92:93], 0
	v_mov_b64_e32 v[94:95], 0
	v_mov_b64_e32 v[96:97], 0
	v_mov_b64_e32 v[98:99], 0
	v_mov_b64_e32 v[100:101], 0
	v_mov_b64_e32 v[102:103], 0
	v_mov_b64_e32 v[104:105], 0
	v_mov_b64_e32 v[106:107], 0
	v_mov_b64_e32 v[108:109], 0
	v_mov_b64_e32 v[110:111], 0
	v_mov_b64_e32 v[112:113], 0
	v_mov_b64_e32 v[114:115], 0
	v_mov_b64_e32 v[116:117], 0
	v_mov_b64_e32 v[118:119], 0
	v_mov_b64_e32 v[120:121], 0
	v_mov_b64_e32 v[122:123], 0
	v_mov_b64_e32 v[124:125], 0
	v_mov_b64_e32 v[126:127], 0

.LBB0_781:
	s_andn2_b64 vcc, exec, s[36:37]
	s_cbranch_vccnz .LBB0_784
	s_add_u32 s44, s10, 0x80
	s_addc_u32 s45, s11, 0
	s_add_u32 s46, s46, 0x100
	s_addc_u32 s47, s47, 0
	s_mov_b32 s10, 0
	v_mov_b64_e32 v[0:1], 0
	v_mov_b64_e32 v[2:3], 0
	v_mov_b64_e32 v[4:5], 0
	v_mov_b64_e32 v[6:7], 0
	v_mov_b64_e32 v[8:9], 0
	v_mov_b64_e32 v[10:11], 0
	v_mov_b64_e32 v[12:13], 0
	v_mov_b64_e32 v[14:15], 0
	v_mov_b64_e32 v[16:17], 0
	v_mov_b64_e32 v[18:19], 0
	v_mov_b64_e32 v[20:21], 0
	v_mov_b64_e32 v[22:23], 0
	v_mov_b64_e32 v[24:25], 0
	v_mov_b64_e32 v[26:27], 0
	v_mov_b64_e32 v[28:29], 0
	v_mov_b64_e32 v[30:31], 0
	v_mov_b64_e32 v[32:33], 0
	v_mov_b64_e32 v[34:35], 0
	v_mov_b64_e32 v[36:37], 0
	v_mov_b64_e32 v[38:39], 0
	v_mov_b64_e32 v[40:41], 0
	v_mov_b64_e32 v[42:43], 0
	v_mov_b64_e32 v[44:45], 0
	v_mov_b64_e32 v[46:47], 0
	v_mov_b64_e32 v[48:49], 0
	v_mov_b64_e32 v[50:51], 0
	v_mov_b64_e32 v[52:53], 0
	v_mov_b64_e32 v[54:55], 0
	v_mov_b64_e32 v[56:57], 0
	v_mov_b64_e32 v[58:59], 0
	v_mov_b64_e32 v[60:61], 0
	v_mov_b64_e32 v[62:63], 0
	v_mov_b64_e32 v[64:65], 0
	v_mov_b64_e32 v[66:67], 0
	v_mov_b64_e32 v[68:69], 0
	v_mov_b64_e32 v[70:71], 0
	v_mov_b64_e32 v[72:73], 0
	v_mov_b64_e32 v[74:75], 0
	v_mov_b64_e32 v[76:77], 0
	v_mov_b64_e32 v[78:79], 0
	v_mov_b64_e32 v[80:81], 0
	v_mov_b64_e32 v[82:83], 0
	v_mov_b64_e32 v[84:85], 0
	v_mov_b64_e32 v[86:87], 0
	v_mov_b64_e32 v[88:89], 0
	v_mov_b64_e32 v[90:91], 0
	v_mov_b64_e32 v[92:93], 0
	v_mov_b64_e32 v[94:95], 0
	v_mov_b64_e32 v[96:97], 0
	v_mov_b64_e32 v[98:99], 0
	v_mov_b64_e32 v[100:101], 0
	v_mov_b64_e32 v[102:103], 0
	v_mov_b64_e32 v[104:105], 0
	v_mov_b64_e32 v[106:107], 0
	v_mov_b64_e32 v[108:109], 0
	v_mov_b64_e32 v[110:111], 0
	v_mov_b64_e32 v[112:113], 0
	v_mov_b64_e32 v[114:115], 0
	v_mov_b64_e32 v[116:117], 0
	v_mov_b64_e32 v[118:119], 0
	v_mov_b64_e32 v[120:121], 0
	v_mov_b64_e32 v[122:123], 0
	v_mov_b64_e32 v[124:125], 0
	v_mov_b64_e32 v[126:127], 0

.LBB0_863:
	s_andn2_b64 vcc, exec, s[38:39]
	s_waitcnt lgkmcnt(0)
	s_cbranch_vccnz .LBB0_866
	s_add_u32 s44, s10, 0x80
	s_addc_u32 s45, s11, 0
	s_add_u32 s46, s46, 0x100
	s_addc_u32 s47, s47, 0
	s_mov_b32 s10, 0
	v_mov_b64_e32 v[0:1], 0
	v_mov_b64_e32 v[2:3], 0
	v_mov_b64_e32 v[4:5], 0
	v_mov_b64_e32 v[6:7], 0
	v_mov_b64_e32 v[8:9], 0
	v_mov_b64_e32 v[10:11], 0
	v_mov_b64_e32 v[12:13], 0
	v_mov_b64_e32 v[14:15], 0
	v_mov_b64_e32 v[16:17], 0
	v_mov_b64_e32 v[18:19], 0
	v_mov_b64_e32 v[20:21], 0
	v_mov_b64_e32 v[22:23], 0
	v_mov_b64_e32 v[24:25], 0
	v_mov_b64_e32 v[26:27], 0
	v_mov_b64_e32 v[28:29], 0
	v_mov_b64_e32 v[30:31], 0
	v_mov_b64_e32 v[32:33], 0
	v_mov_b64_e32 v[34:35], 0
	v_mov_b64_e32 v[36:37], 0
	v_mov_b64_e32 v[38:39], 0
	v_mov_b64_e32 v[40:41], 0
	v_mov_b64_e32 v[42:43], 0
	v_mov_b64_e32 v[44:45], 0
	v_mov_b64_e32 v[46:47], 0
	v_mov_b64_e32 v[48:49], 0
	v_mov_b64_e32 v[50:51], 0
	v_mov_b64_e32 v[52:53], 0
	v_mov_b64_e32 v[54:55], 0
	v_mov_b64_e32 v[56:57], 0
	v_mov_b64_e32 v[58:59], 0
	v_mov_b64_e32 v[60:61], 0
	v_mov_b64_e32 v[62:63], 0
	v_mov_b64_e32 v[64:65], 0
	v_mov_b64_e32 v[66:67], 0
	v_mov_b64_e32 v[68:69], 0
	v_mov_b64_e32 v[70:71], 0
	v_mov_b64_e32 v[72:73], 0
	v_mov_b64_e32 v[74:75], 0
	v_mov_b64_e32 v[76:77], 0
	v_mov_b64_e32 v[78:79], 0
	v_mov_b64_e32 v[80:81], 0
	v_mov_b64_e32 v[82:83], 0
	v_mov_b64_e32 v[84:85], 0
	v_mov_b64_e32 v[86:87], 0
	v_mov_b64_e32 v[88:89], 0
	v_mov_b64_e32 v[90:91], 0
	v_mov_b64_e32 v[92:93], 0
	v_mov_b64_e32 v[94:95], 0
	v_mov_b64_e32 v[96:97], 0
	v_mov_b64_e32 v[98:99], 0
	v_mov_b64_e32 v[100:101], 0
	v_mov_b64_e32 v[102:103], 0
	v_mov_b64_e32 v[104:105], 0
	v_mov_b64_e32 v[106:107], 0
	v_mov_b64_e32 v[108:109], 0
	v_mov_b64_e32 v[110:111], 0
	v_mov_b64_e32 v[112:113], 0
	v_mov_b64_e32 v[114:115], 0
	v_mov_b64_e32 v[116:117], 0
	v_mov_b64_e32 v[118:119], 0
	v_mov_b64_e32 v[120:121], 0
	v_mov_b64_e32 v[122:123], 0
	v_mov_b64_e32 v[124:125], 0
	v_mov_b64_e32 v[126:127], 0

.LBB0_959:
	s_andn2_b64 vcc, exec, s[24:25]
	s_cbranch_vccnz .LBB0_963
	s_add_u32 s46, s10, 0x80
	s_addc_u32 s47, s11, 0
	s_add_u32 s48, s48, 0x100
	s_addc_u32 s49, s49, 0
	s_mov_b32 s10, 0
	v_mov_b64_e32 v[0:1], 0
	v_mov_b64_e32 v[2:3], 0
	v_mov_b64_e32 v[4:5], 0
	v_mov_b64_e32 v[6:7], 0
	v_mov_b64_e32 v[8:9], 0
	v_mov_b64_e32 v[10:11], 0
	v_mov_b64_e32 v[12:13], 0
	v_mov_b64_e32 v[14:15], 0
	v_mov_b64_e32 v[16:17], 0
	v_mov_b64_e32 v[18:19], 0
	v_mov_b64_e32 v[20:21], 0
	v_mov_b64_e32 v[22:23], 0
	v_mov_b64_e32 v[24:25], 0
	v_mov_b64_e32 v[26:27], 0
	v_mov_b64_e32 v[28:29], 0
	v_mov_b64_e32 v[30:31], 0
	v_mov_b64_e32 v[32:33], 0
	v_mov_b64_e32 v[34:35], 0
	v_mov_b64_e32 v[36:37], 0
	v_mov_b64_e32 v[38:39], 0
	v_mov_b64_e32 v[40:41], 0
	v_mov_b64_e32 v[42:43], 0
	v_mov_b64_e32 v[44:45], 0
	v_mov_b64_e32 v[46:47], 0
	v_mov_b64_e32 v[48:49], 0
	v_mov_b64_e32 v[50:51], 0
	v_mov_b64_e32 v[52:53], 0
	v_mov_b64_e32 v[54:55], 0
	v_mov_b64_e32 v[56:57], 0
	v_mov_b64_e32 v[58:59], 0
	v_mov_b64_e32 v[60:61], 0
	v_mov_b64_e32 v[62:63], 0
	v_mov_b64_e32 v[64:65], 0
	v_mov_b64_e32 v[66:67], 0
	v_mov_b64_e32 v[68:69], 0
	v_mov_b64_e32 v[70:71], 0
	v_mov_b64_e32 v[72:73], 0
	v_mov_b64_e32 v[74:75], 0
	v_mov_b64_e32 v[76:77], 0
	v_mov_b64_e32 v[78:79], 0
	v_mov_b64_e32 v[80:81], 0
	v_mov_b64_e32 v[82:83], 0
	v_mov_b64_e32 v[84:85], 0
	v_mov_b64_e32 v[86:87], 0
	v_mov_b64_e32 v[88:89], 0
	v_mov_b64_e32 v[90:91], 0
	v_mov_b64_e32 v[92:93], 0
	v_mov_b64_e32 v[94:95], 0
	v_mov_b64_e32 v[96:97], 0
	v_mov_b64_e32 v[98:99], 0
	v_mov_b64_e32 v[100:101], 0
	v_mov_b64_e32 v[102:103], 0
	v_mov_b64_e32 v[104:105], 0
	v_mov_b64_e32 v[106:107], 0
	v_mov_b64_e32 v[108:109], 0
	v_mov_b64_e32 v[110:111], 0
	v_mov_b64_e32 v[112:113], 0
	v_mov_b64_e32 v[114:115], 0
	v_mov_b64_e32 v[116:117], 0
	v_mov_b64_e32 v[118:119], 0
	v_mov_b64_e32 v[120:121], 0
	v_mov_b64_e32 v[122:123], 0
	v_mov_b64_e32 v[124:125], 0
	v_mov_b64_e32 v[126:127], 0

.LBB0_1042:
	s_andn2_b64 vcc, exec, s[36:37]
	s_waitcnt lgkmcnt(0)
	s_cbranch_vccnz .LBB0_1045
	s_add_u32 s42, s10, 0x80
	s_addc_u32 s43, s11, 0
	s_add_u32 s44, s44, 0x100
	s_addc_u32 s45, s45, 0
	s_mov_b32 s10, 0
	v_mov_b64_e32 v[0:1], 0
	v_mov_b64_e32 v[2:3], 0
	v_mov_b64_e32 v[4:5], 0
	v_mov_b64_e32 v[6:7], 0
	v_mov_b64_e32 v[8:9], 0
	v_mov_b64_e32 v[10:11], 0
	v_mov_b64_e32 v[12:13], 0
	v_mov_b64_e32 v[14:15], 0
	v_mov_b64_e32 v[16:17], 0
	v_mov_b64_e32 v[18:19], 0
	v_mov_b64_e32 v[20:21], 0
	v_mov_b64_e32 v[22:23], 0
	v_mov_b64_e32 v[24:25], 0
	v_mov_b64_e32 v[26:27], 0
	v_mov_b64_e32 v[28:29], 0
	v_mov_b64_e32 v[30:31], 0
	v_mov_b64_e32 v[32:33], 0
	v_mov_b64_e32 v[34:35], 0
	v_mov_b64_e32 v[36:37], 0
	v_mov_b64_e32 v[38:39], 0
	v_mov_b64_e32 v[40:41], 0
	v_mov_b64_e32 v[42:43], 0
	v_mov_b64_e32 v[44:45], 0
	v_mov_b64_e32 v[46:47], 0
	v_mov_b64_e32 v[48:49], 0
	v_mov_b64_e32 v[50:51], 0
	v_mov_b64_e32 v[52:53], 0
	v_mov_b64_e32 v[54:55], 0
	v_mov_b64_e32 v[56:57], 0
	v_mov_b64_e32 v[58:59], 0
	v_mov_b64_e32 v[60:61], 0
	v_mov_b64_e32 v[62:63], 0
	v_mov_b64_e32 v[64:65], 0
	v_mov_b64_e32 v[66:67], 0
	v_mov_b64_e32 v[68:69], 0
	v_mov_b64_e32 v[70:71], 0
	v_mov_b64_e32 v[72:73], 0
	v_mov_b64_e32 v[74:75], 0
	v_mov_b64_e32 v[76:77], 0
	v_mov_b64_e32 v[78:79], 0
	v_mov_b64_e32 v[80:81], 0
	v_mov_b64_e32 v[82:83], 0
	v_mov_b64_e32 v[84:85], 0
	v_mov_b64_e32 v[86:87], 0
	v_mov_b64_e32 v[88:89], 0
	v_mov_b64_e32 v[90:91], 0
	v_mov_b64_e32 v[92:93], 0
	v_mov_b64_e32 v[94:95], 0
	v_mov_b64_e32 v[96:97], 0
	v_mov_b64_e32 v[98:99], 0
	v_mov_b64_e32 v[100:101], 0
	v_mov_b64_e32 v[102:103], 0
	v_mov_b64_e32 v[104:105], 0
	v_mov_b64_e32 v[106:107], 0
	v_mov_b64_e32 v[108:109], 0
	v_mov_b64_e32 v[110:111], 0
	v_mov_b64_e32 v[112:113], 0
	v_mov_b64_e32 v[114:115], 0
	v_mov_b64_e32 v[116:117], 0
	v_mov_b64_e32 v[118:119], 0
	v_mov_b64_e32 v[120:121], 0
	v_mov_b64_e32 v[122:123], 0
	v_mov_b64_e32 v[124:125], 0
	v_mov_b64_e32 v[126:127], 0
